# combo17 + E55: same mixing in PB (half of the CUs run their SSD state-delta item before their mLSTM one)
# speedup vs baseline: 1.0112x; 1.0010x over previous
.LBB0_263:
	s_nop 0
	v_readlane_b32 s0, v255, 0
	v_readlane_b32 s1, v255, 1
	s_andn2_b64 vcc, exec, s[0:1]
	s_cbranch_vccnz .LBB0_266
	v_readlane_b32 s0, v251, 63
	v_readlane_b32 s1, v252, 0
	s_andn2_b64 vcc, exec, s[0:1]
	s_mov_b32 s12, s57
	s_mov_b32 s13, s57
	v_readlane_b32 s14, v253, 61
	s_mov_b32 s15, s57
	s_cbranch_vccnz .Lpb_not
	s_movk_i32 s32, 0x7fff
	s_cmpk_lg_u32 s36, 0x100
	s_cbranch_scc1 .LBB0_401
	s_movk_i32 s32, 2
	s_bitcmp1_b32 s57, 5
	s_cbranch_scc0 .LBB0_401
	s_addk_i32 s15, 0x100
	s_addk_i32 s14, 0x100
	s_addk_i32 s13, 0x100
	s_addk_i32 s12, 0x100
	s_branch .LBB0_401
.Lpb_not:
.LBB0_265:
	s_mov_b64 s[8:9], -1
.LBB0_266:
	s_mov_b64 s[0:1], 0

.LBB0_400:
	s_add_i32 s15, s15, s36
	s_add_i32 s14, s14, s36
	s_add_i32 s13, s13, s36
	s_add_i32 s12, s12, s36
	s_add_i32 s32, s32, -1
	s_waitcnt lgkmcnt(0)
	s_cmp_eq_u32 s32, 0
	s_cbranch_scc1 .LBB0_265
	s_cmpk_gt_i32 s15, 0x1ff
	s_cbranch_scc0 .LBB0_401
	s_cmpk_gt_u32 s32, 0x1000
	s_cbranch_scc1 .LBB0_265
	s_addk_i32 s15, -512
	s_addk_i32 s14, -512
	s_addk_i32 s13, -512
	s_addk_i32 s12, -512
